# v15: v11 + attention B loop-invariant hoisting: stage-store LDS addresses (v237/v238 + offsets) and dilation-4 stage-load row offsets (v239..v243, saddr loads) computed once per phase
# baseline (speedup 1.0000x reference)
; template <int MIX, bool DRY = false>
; __device__ __forceinline__ void attn_phase(LAS unsigned char* lds, const bf16_t* Qb, const bf16_t* Kb, const bf16_t* Vb, bf16_t* Gb, const float* qg, const float* kg, const float* sinks) {
;     ...
;     for (int g = 0; g < NG; ++g) { float mq = fabsf(qg[g * 64 + lane0]), mk = fabsf(kg[g * 64 + lane0]);
; #pragma unroll
;         for (int o = 1; o < 64; o <<= 1) { mq = fmaxf(mq, __shfl_xor(mq, o)); mk = fmaxf(mk, __shfl_xor(mk, o)); }
;         Mb = fmaxf(Mb, 8.0f * mq * mk); }
.LBB0_393:
	s_or_b64 exec, exec, s[4:5]
	v_readlane_b32 s6, v253, 35
	v_readlane_b32 s7, v253, 36
	s_mov_b64 s[4:5], -1
	s_and_b64 vcc, exec, s[36:37]
	s_waitcnt lgkmcnt(0)
	v_cndmask_b32_e64 v0, 0, 1, s[6:7]
	v_cmp_ne_u32_e64 s[6:7], 1, v0
	s_barrier
	s_nop 0
	v_writelane_b32 v251, s6, 53
	s_nop 1
	v_writelane_b32 v251, s7, 54
	s_cbranch_vccnz .LBB0_484
	v_readlane_b32 s4, v251, 50
	v_readlane_b32 s5, v251, 51
	s_mov_b32 s1, s5
	s_lshl_b64 s[4:5], s[0:1], 2
	v_mov_b32_e32 v202, v196
	v_ashrrev_i32_e32 v237, 4, v202
	v_lshlrev_b32_e32 v238, 2, v237
	v_and_b32_e32 v238, 4, v238
	v_xor_b32_e32 v237, v237, v202
	v_bitop3_b32 v237, v237, v238, 7 bitop3:0x6c
	v_ashrrev_i32_e32 v238, 3, v202
	v_lshlrev_b32_e32 v238, 7, v238
	v_lshl_or_b32 v237, v237, 4, v238
	v_add_u32_e32 v238, 0x1a800, v237
	v_add_u32_e32 v237, 0x10800, v237
	v_ashrrev_i32_e32 v239, 3, v202
	v_lshlrev_b32_e32 v240, 4, v202
	v_and_b32_e32 v240, 0x70, v240
	v_lshl_add_u32 v239, v239, 11, v240
	v_add_u32_e32 v240, 0x20000, v239
	v_add_u32_e32 v242, 0x10200, v239
	v_add_u32_e32 v243, 0x30200, v239
	v_add_u32_e32 v241, 0x40000, v239
	v_subrev_u32_e32 v244, 0xfe00, v239
	v_cmp_gt_i32_e32 vcc, 0x100, v202
	s_nop 1
	v_cndmask_b32_e32 v241, v244, v241, vcc
	s_add_u32 s0, s74, s4
	s_addc_u32 s1, s75, s5
	v_and_b32_e32 v0, 63, v202
	v_lshlrev_b32_e32 v0, 2, v0
	global_load_dword v1, v0, s[0:1]
	global_load_dword v2, v0, s[0:1] offset:256
	s_add_u32 s4, s76, s4
	s_addc_u32 s5, s77, s5
	global_load_dword v3, v0, s[4:5]
	global_load_dword v4, v0, s[4:5] offset:256
	global_load_dword v5, v0, s[4:5] offset:512
	s_nop 0
	global_load_dword v0, v0, s[0:1] offset:512
	v_and_b32_e32 v6, 64, v197
	v_xor_b32_e32 v7, 1, v197
	v_add_u32_e32 v6, 64, v6
	v_xor_b32_e32 v8, 2, v197
	v_cmp_lt_i32_e32 vcc, v7, v6
	v_xor_b32_e32 v9, 4, v197
	v_xor_b32_e32 v10, 8, v197
	v_cndmask_b32_e32 v7, v197, v7, vcc
	v_cmp_lt_i32_e32 vcc, v8, v6
	v_xor_b32_e32 v11, 16, v197
	v_xor_b32_e32 v12, 32, v197
	v_cndmask_b32_e32 v8, v197, v8, vcc
	v_cmp_lt_i32_e32 vcc, v9, v6
	v_lshlrev_b32_e32 v7, 2, v7
	v_lshlrev_b32_e32 v8, 2, v8
	v_cndmask_b32_e32 v9, v197, v9, vcc
	v_cmp_lt_i32_e32 vcc, v10, v6
	v_lshlrev_b32_e32 v9, 2, v9
	v_readlane_b32 s0, v251, 53
	v_cndmask_b32_e32 v10, v197, v10, vcc
	v_cmp_lt_i32_e32 vcc, v11, v6
	v_lshlrev_b32_e32 v10, 2, v10
	v_readlane_b32 s1, v251, 54
	v_cndmask_b32_e32 v11, v197, v11, vcc
	v_cmp_lt_i32_e32 vcc, v12, v6
	v_lshlrev_b32_e32 v11, 2, v11
	v_readfirstlane_b32 s4, v202
	v_cndmask_b32_e32 v6, v197, v12, vcc
	v_lshlrev_b32_e32 v12, 2, v6
	s_and_b64 vcc, exec, s[0:1]
	s_waitcnt vmcnt(0)
	v_and_b32_e32 v6, 0x7fffffff, v1
	s_waitcnt vmcnt(4)
	v_and_b32_e32 v13, 0x7fffffff, v2
	ds_bpermute_b32 v6, v7, v6
	ds_bpermute_b32 v13, v7, v13
	s_waitcnt vmcnt(3)
	v_and_b32_e32 v14, 0x7fffffff, v3
	s_waitcnt vmcnt(2)
	v_and_b32_e32 v15, 0x7fffffff, v4
	ds_bpermute_b32 v14, v7, v14
	ds_bpermute_b32 v15, v7, v15
	v_max_f32_e64 v1, |v1|, |v1|
	v_max_f32_e64 v2, |v2|, |v2|
	s_waitcnt vmcnt(0)
	v_and_b32_e32 v16, 0x7fffffff, v0
	s_waitcnt lgkmcnt(3)
	v_max_f32_e32 v6, v6, v6
	s_waitcnt lgkmcnt(2)
	v_max_f32_e32 v13, v13, v13
	v_and_b32_e32 v17, 0x7fffffff, v5
	ds_bpermute_b32 v16, v7, v16
	v_max_f32_e32 v1, v1, v6
	v_max_f32_e32 v2, v2, v13
	ds_bpermute_b32 v7, v7, v17
	s_waitcnt lgkmcnt(3)
	v_max_f32_e32 v6, v14, v14
	ds_bpermute_b32 v13, v8, v1
	s_waitcnt lgkmcnt(3)
	v_max_f32_e32 v14, v15, v15
	ds_bpermute_b32 v15, v8, v2
	v_max_f32_e64 v3, |v3|, |v3|
	v_max_f32_e64 v4, |v4|, |v4|
	v_max_f32_e64 v0, |v0|, |v0|
	s_waitcnt lgkmcnt(3)
	v_max_f32_e32 v16, v16, v16
	v_max_f32_e64 v5, |v5|, |v5|
	s_waitcnt lgkmcnt(2)
	v_max_f32_e32 v7, v7, v7
	v_max_f32_e32 v3, v3, v6
	v_max_f32_e32 v4, v4, v14
	v_max_f32_e32 v0, v0, v16
	s_waitcnt lgkmcnt(1)
	v_max_f32_e32 v13, v13, v13
	s_waitcnt lgkmcnt(0)
	v_max_f32_e32 v15, v15, v15
	v_max_f32_e32 v5, v5, v7
	ds_bpermute_b32 v6, v8, v3
	ds_bpermute_b32 v7, v8, v4
	ds_bpermute_b32 v14, v8, v0
	v_max_f32_e32 v1, v1, v13
	v_max_f32_e32 v2, v2, v15
	ds_bpermute_b32 v13, v9, v1
	ds_bpermute_b32 v15, v9, v2
	s_waitcnt lgkmcnt(4)
	v_max_f32_e32 v6, v6, v6
	s_waitcnt lgkmcnt(3)
	v_max_f32_e32 v7, v7, v7
	s_waitcnt lgkmcnt(2)
	v_max_f32_e32 v14, v14, v14
	v_max_f32_e32 v3, v3, v6
	v_max_f32_e32 v4, v4, v7
	v_max_f32_e32 v6, v0, v14
	s_waitcnt lgkmcnt(1)
	v_max_f32_e32 v13, v13, v13
	s_waitcnt lgkmcnt(0)
	v_max_f32_e32 v14, v15, v15
	ds_bpermute_b32 v0, v9, v3
	ds_bpermute_b32 v7, v9, v4
	v_max_f32_e32 v1, v1, v13
	v_max_f32_e32 v2, v2, v14
	ds_bpermute_b32 v13, v10, v1
	ds_bpermute_b32 v14, v10, v2
	s_waitcnt lgkmcnt(3)
	v_max_f32_e32 v0, v0, v0
	s_waitcnt lgkmcnt(2)
	v_max_f32_e32 v7, v7, v7
	v_max_f32_e32 v0, v3, v0
	v_max_f32_e32 v3, v4, v7
	s_waitcnt lgkmcnt(1)
	v_max_f32_e32 v13, v13, v13
	s_waitcnt lgkmcnt(0)
	v_max_f32_e32 v14, v14, v14
	ds_bpermute_b32 v8, v8, v5
	ds_bpermute_b32 v7, v10, v3
	v_max_f32_e32 v1, v1, v13
	v_max_f32_e32 v13, v2, v14
	ds_bpermute_b32 v14, v11, v13
	s_waitcnt lgkmcnt(2)
	v_max_f32_e32 v8, v8, v8
	s_waitcnt lgkmcnt(1)
	v_max_f32_e32 v7, v7, v7
	v_max_f32_e32 v7, v3, v7
	v_max_f32_e32 v5, v5, v8
	s_waitcnt lgkmcnt(0)
	v_max_f32_e32 v3, v14, v14
	ds_bpermute_b32 v14, v9, v6
	ds_bpermute_b32 v8, v9, v5
	v_max_f32_e32 v3, v13, v3
	ds_bpermute_b32 v9, v11, v7
	ds_bpermute_b32 v4, v10, v0
	s_waitcnt lgkmcnt(3)
	v_max_f32_e32 v13, v14, v14
	v_max_f32_e32 v6, v6, v13
	s_waitcnt lgkmcnt(2)
	v_max_f32_e32 v8, v8, v8
	ds_bpermute_b32 v13, v10, v6
	v_max_f32_e32 v8, v5, v8
	ds_bpermute_b32 v10, v10, v8
	s_waitcnt lgkmcnt(3)
	v_max_f32_e32 v5, v9, v9
	v_max_f32_e32 v5, v7, v5
	s_waitcnt lgkmcnt(1)
	v_max_f32_e32 v7, v13, v13
	v_max_f32_e32 v2, v4, v4
	v_max_f32_e32 v6, v6, v7
	s_waitcnt lgkmcnt(0)
	v_max_f32_e32 v7, v10, v10
	ds_bpermute_b32 v4, v11, v1
	v_max_f32_e32 v2, v0, v2
	ds_bpermute_b32 v10, v11, v6
	v_max_f32_e32 v8, v8, v7
	ds_bpermute_b32 v15, v11, v2
	ds_bpermute_b32 v13, v11, v8
	s_waitcnt lgkmcnt(3)
	v_max_f32_e32 v0, v4, v4
	s_waitcnt lgkmcnt(2)
	v_max_f32_e32 v7, v10, v10
	v_max_f32_e32 v0, v1, v0
	s_waitcnt lgkmcnt(1)
	v_max_f32_e32 v1, v15, v15
	v_max_f32_e32 v7, v6, v7
	s_waitcnt lgkmcnt(0)
	v_max_f32_e32 v6, v13, v13
	v_max_f32_e32 v1, v2, v1
	v_max_f32_e32 v6, v8, v6
	ds_bpermute_b32 v4, v12, v0
	ds_bpermute_b32 v2, v12, v1
	ds_bpermute_b32 v11, v12, v3
	ds_bpermute_b32 v9, v12, v5
	ds_bpermute_b32 v10, v12, v7
	ds_bpermute_b32 v8, v12, v6
	s_cbranch_vccnz .LBB0_404
; template <int MIX, bool DRY = false>
; __device__ __forceinline__ void attn_phase(LAS unsigned char* lds, const bf16_t* Qb, const bf16_t* Kb, const bf16_t* Vb, bf16_t* Gb, const float* qg, const float* kg, const float* sinks) {
;     ...
;     constexpr int NJ = MIX == 0 ? 3 : 5;
;     constexpr bool PF = (MIX == 0) ? PF_A : PF_B;
;     u32x4 kreg[NJ], vreg[NJ];
;     if ((PF || MIX == 1) && (int)blockIdx.x < NUNITS) STAGE_LOAD(blockIdx.x, 0)
;     if (MIX == 1 && (int)blockIdx.x < NUNITS) STAGE_STORE(0)
	v_mov_b32_e32 v12, v202
	v_readlane_b32 s0, v253, 41
	v_ashrrev_i32_e32 v20, 3, v12
	v_lshlrev_b32_e32 v12, 4, v12
	v_and_b32_e32 v112, 0x70, v12
	v_readlane_b32 s1, v253, 42
	v_min_i32_e32 v16, 0xff, v20
	v_readlane_b32 s6, v253, 50
	v_lshl_add_u64 v[12:13], s[0:1], 0, v[112:113]
	v_readlane_b32 s0, v253, 43
	v_readlane_b32 s1, v253, 44
	v_readlane_b32 s7, v253, 51
	s_nop 0
	v_lshl_add_u64 v[14:15], s[0:1], 0, v[112:113]
	v_readlane_b32 s0, v253, 45
	s_nop 1
	v_add_u32_e32 v16, s0, v16
	v_ashrrev_i32_e32 v17, 31, v16
	v_lshlrev_b64 v[16:17], 8, v[16:17]
	v_lshl_add_u64 v[16:17], v[16:17], 0, s[6:7]
	v_lshlrev_b64 v[16:17], 1, v[16:17]
	v_lshl_add_u64 v[18:19], v[12:13], 0, v[16:17]
	v_lshl_add_u64 v[16:17], v[14:15], 0, v[16:17]
	global_load_dwordx4 v[114:117], v[18:19], off
	global_load_dwordx4 v[118:121], v[16:17], off
	v_min_i32_e32 v16, 0xbf, v20
	v_readlane_b32 s0, v253, 46
	s_nop 1
	v_add_u32_e32 v16, s0, v16
	v_ashrrev_i32_e32 v17, 31, v16
	v_lshlrev_b64 v[16:17], 8, v[16:17]
	v_lshl_add_u64 v[16:17], v[16:17], 0, s[6:7]
	v_lshlrev_b64 v[16:17], 1, v[16:17]
	v_lshl_add_u64 v[18:19], v[12:13], 0, v[16:17]
	v_lshl_add_u64 v[16:17], v[14:15], 0, v[16:17]
	global_load_dwordx4 v[122:125], v[18:19], off
	global_load_dwordx4 v[126:129], v[16:17], off
	v_min_i32_e32 v16, 0x7f, v20
	v_readlane_b32 s0, v253, 48
	s_nop 1
	v_add_u32_e32 v16, s0, v16
	v_ashrrev_i32_e32 v17, 31, v16
	v_lshlrev_b64 v[16:17], 8, v[16:17]
	v_lshl_add_u64 v[16:17], v[16:17], 0, s[6:7]
	v_lshlrev_b64 v[16:17], 1, v[16:17]
	v_lshl_add_u64 v[18:19], v[12:13], 0, v[16:17]
	v_lshl_add_u64 v[16:17], v[14:15], 0, v[16:17]
	global_load_dwordx4 v[130:133], v[18:19], off
	global_load_dwordx4 v[134:137], v[16:17], off
	v_min_i32_e32 v16, 63, v20
	v_readlane_b32 s0, v253, 47
	s_nop 1
	v_add_u32_e32 v16, s0, v16
	v_ashrrev_i32_e32 v17, 31, v16
	v_lshlrev_b64 v[16:17], 8, v[16:17]
	v_lshl_add_u64 v[16:17], v[16:17], 0, s[6:7]
	v_lshlrev_b64 v[16:17], 1, v[16:17]
	v_lshl_add_u64 v[18:19], v[12:13], 0, v[16:17]
	v_lshl_add_u64 v[16:17], v[14:15], 0, v[16:17]
	global_load_dwordx4 v[138:141], v[18:19], off
	global_load_dwordx4 v[142:145], v[16:17], off
	v_min_i32_e32 v16, -1, v20
	v_readlane_b32 s0, v253, 49
	s_nop 1
	v_add_u32_e32 v16, s0, v16
	v_ashrrev_i32_e32 v17, 31, v16
	v_lshlrev_b64 v[16:17], 8, v[16:17]
	v_lshl_add_u64 v[16:17], v[16:17], 0, s[6:7]
	v_lshlrev_b64 v[16:17], 1, v[16:17]
	v_lshl_add_u64 v[12:13], v[12:13], 0, v[16:17]
	v_lshl_add_u64 v[14:15], v[14:15], 0, v[16:17]
	global_load_dwordx4 v[146:149], v[12:13], off
	global_load_dwordx4 v[150:153], v[14:15], off
	v_mov_b32_e32 v12, v202
	s_movk_i32 s0, 0x100
	v_ashrrev_i32_e32 v13, 3, v12
	v_cmp_gt_i32_e32 vcc, s0, v13
	s_and_saveexec_b64 s[0:1], vcc
	s_cbranch_execz .LBB0_397
	v_ashrrev_i32_e32 v15, 4, v12
	v_lshlrev_b32_e32 v16, 2, v15
	v_and_b32_e32 v16, 4, v16
	v_xor_b32_e32 v15, v15, v12
	v_lshlrev_b32_e32 v14, 7, v13
	v_bitop3_b32 v15, v15, v16, 7 bitop3:0x6c
	v_lshl_or_b32 v14, v15, 4, v14
	v_add_u32_e32 v14, 0, v14
	v_add_u32_e32 v15, 0x10800, v14
	v_add_u32_e32 v14, 0x1a800, v14
	s_waitcnt vmcnt(9)
	ds_write_b128 v15, v[114:117]
	s_waitcnt vmcnt(8)
	ds_write_b128 v14, v[118:121]

; template <int MIX, bool DRY = false>
; __device__ __forceinline__ void attn_phase(LAS unsigned char* lds, const bf16_t* Qb, const bf16_t* Kb, const bf16_t* Vb, bf16_t* Gb, const float* qg, const float* kg, const float* sinks) {
;     ...
;             const int nrows = MIX == 0 ? 192 : (st == 0 ? 256 : 320);
;             const int ntask = (MIX == 0 || st == 0) ? 16 : 8;
;             constexpr bool PRE0 = (MIX == 1);
;             if (!PF && !(PRE0 && st == 0)) STAGE_LOAD(unit, st)
;     ...
;             bf16x8 qn[4];
;             { TASK_DECODE(wave) (void)f0; (void)tb0; const bf16_t* qp_ = Qg + (rowb + t0 + tl) * 1024 + (kvh * REP + hr) * 64 + 8 * h;
; #pragma unroll
;               for (int s = 0; s < 4; ++s) qn[s] = *(const bf16x8*)(qp_ + 16 * s); }
;             if (!(PRE0 && st == 0)) {
;                 __syncthreads();
;                 STAGE_STORE(st)
;             }
.LBB0_414:
	s_cmp_eq_u32 s26, 0
	s_cselect_b64 s[14:15], -1, 0
	s_cmp_lg_u32 s26, 0
	s_cselect_b64 s[8:9], -1, 0
	s_and_b64 vcc, exec, s[14:15]
	v_mov_b32_e32 v112, v225
	v_readlane_b32 s16, v251, 57
	s_cbranch_vccnz .LBB0_416
	s_lshl_b32 s10, s26, 1
	s_add_i32 s11, s25, s10
	s_mov_b32 s78, s11
	s_ashr_i32 s79, s11, 31
	s_lshl_b64 s[78:79], s[78:79], 9
	s_lshl_b64 s[74:75], s[12:13], 1
	s_add_u32 s74, s74, s78
	s_addc_u32 s75, s75, s79
	s_add_u32 s76, s74, s6
	s_addc_u32 s77, s75, s7
	s_add_u32 s74, s74, s4
	s_addc_u32 s75, s75, s5
	global_load_dwordx4 v[114:117], v239, s[74:75]
	global_load_dwordx4 v[118:121], v239, s[76:77]
	global_load_dwordx4 v[122:125], v240, s[74:75]
	global_load_dwordx4 v[126:129], v240, s[76:77]
	global_load_dwordx4 v[130:133], v241, s[74:75]
	global_load_dwordx4 v[134:137], v241, s[76:77]
	global_load_dwordx4 v[138:141], v242, s[74:75]
	global_load_dwordx4 v[142:145], v242, s[76:77]
	global_load_dwordx4 v[146:149], v243, s[74:75]
	global_load_dwordx4 v[150:153], v243, s[76:77]
	v_add_u32_e32 v112, s10, v224
	v_readlane_b32 s16, v251, 55
	s_nop 0
.LBB0_416:
	s_and_b64 s[10:11], exec, s[14:15]
	s_cselect_b32 s10, 0, 0x4000000
	v_readlane_b32 s28, v252, 22
	v_readlane_b32 s29, v252, 23
	s_add_u32 s10, s28, s10
	s_addc_u32 s11, s29, 0
	v_lshl_add_u64 v[16:17], s[82:83], 0, v[112:113]
	s_add_i32 s16, s16, s23
	v_lshlrev_b64 v[16:17], 11, v[16:17]
	s_lshl_b32 s16, s16, 6
	v_lshl_add_u64 v[16:17], s[10:11], 0, v[16:17]
	s_ashr_i32 s17, s16, 31
	v_lshl_add_u64 v[16:17], s[16:17], 1, v[16:17]
	v_lshlrev_b32_e32 v112, 1, v190
	v_lshl_add_u64 v[16:17], v[16:17], 0, v[112:113]
	global_load_dwordx4 v[182:185], v[16:17], off
	global_load_dwordx4 v[178:181], v[16:17], off offset:32
	global_load_dwordx4 v[174:177], v[16:17], off offset:64
	global_load_dwordx4 v[170:173], v[16:17], off offset:96
	v_cndmask_b32_e64 v16, 0, 1, s[8:9]
	v_cmp_ne_u32_e64 s[72:73], 1, v16
	s_andn2_b64 vcc, exec, s[8:9]
	s_cbranch_vccnz .LBB0_428
	s_barrier
	s_waitcnt vmcnt(13)
	ds_write_b128 v237, v[114:117]
	s_waitcnt vmcnt(12)
	ds_write_b128 v238, v[118:121]
	s_waitcnt vmcnt(11)
	ds_write_b128 v237, v[122:125] offset:8192
	s_waitcnt vmcnt(10)
	ds_write_b128 v238, v[126:129] offset:8192
	s_waitcnt vmcnt(9)
	ds_write_b128 v237, v[130:133] offset:16384
	s_waitcnt vmcnt(8)
	ds_write_b128 v238, v[134:137] offset:16384
	s_waitcnt vmcnt(7)
	ds_write_b128 v237, v[138:141] offset:24576
	s_waitcnt vmcnt(6)
	ds_write_b128 v238, v[142:145] offset:24576
	s_waitcnt vmcnt(5)
	ds_write_b128 v237, v[146:149] offset:32768
	s_waitcnt vmcnt(4)
	ds_write_b128 v238, v[150:153] offset:32768

; #define LAS __attribute__((address_space(3)))
; __device__ __forceinline__ unsigned pkbf(float lo, float hi) { f32x2v v = {lo, hi}; return __builtin_bit_cast(unsigned, __builtin_convertvector(v, bf2_t)); }
; __device__ __forceinline__ float bflo(unsigned w) { return __uint_as_float(w << 16); }
; __device__ __forceinline__ float bfhi(unsigned w) { return __uint_as_float(w & 0xffff0000u); }
; template <int MIX, bool DRY = false>
; __device__ __forceinline__ void attn_phase(LAS unsigned char* lds, const bf16_t* Qb, const bf16_t* Kb, const bf16_t* Vb, bf16_t* Gb, const float* qg, const float* kg, const float* sinks) {
;     ...
;             __syncthreads();
;             const bool more = unit + (int)gridDim.x < NUNITS;
;             STAGE_LOAD(more ? unit + (int)gridDim.x : unit, 0)
; #pragma unroll 4
;             for (int it = 0; it < (DRY ? 0 : 8); ++it) {
;                 const int item = it * 512 + tidu, row = item >> 3, dg = item & 7, hr = row / CT, tl = row % CT;
;                 const int f = ((tl >> 1) ^ (tl >> 4) ^ (hr << 2)) & 15, head = kvh * REP + hr;
;                 const LAS unsigned char* orow = Oacc + row * 128;
;                 const u32x2 o0 = *(const LAS u32x2*)(orow + (((2 * dg) ^ f) << 3)), o1 = *(const LAS u32x2*)(orow + (((2 * dg + 1) ^ f) << 3));
;                 const float inv = 1.0f / lacc[row];
;                 u32x4* gp = (u32x4*)(Gb + (rowb + t0 + tl) * 1024 + head * 64 + 8 * dg);
;                 const u32x4 gv = *gp;
;                 u32x4 w;
;                 w.x = pkbf(bflo(o0.x) * inv * bflo(gv.x), bfhi(o0.x) * inv * bfhi(gv.x)); w.y = pkbf(bflo(o0.y) * inv * bflo(gv.y), bfhi(o0.y) * inv * bfhi(gv.y));
;                 w.z = pkbf(bflo(o1.x) * inv * bflo(gv.z), bfhi(o1.x) * inv * bfhi(gv.z)); w.w = pkbf(bflo(o1.y) * inv * bflo(gv.w), bfhi(o1.y) * inv * bfhi(gv.w));
;                 *gp = w;
;             }
.LBB0_469:
	v_readlane_b32 s7, v250, 1
	s_add_i32 s6, s7, s80
	s_cmpk_lt_i32 s6, 0x400
	s_cselect_b64 s[0:1], -1, 0
	s_and_b64 s[4:5], s[0:1], exec
	s_cselect_b32 s7, s6, s7
	s_ashr_i32 s4, s7, 3
	s_andn2_b32 s4, s4, 31
	v_readlane_b32 s5, v250, 5
	s_add_i32 s4, s4, s5
	v_readlane_b32 s5, v250, 4
	s_or_b32 s8, s5, s4
	v_readlane_b32 s4, v253, 39
	v_readlane_b32 s5, v253, 40
	s_and_b64 s[4:5], s[4:5], exec
	s_cselect_b32 s4, s8, s7
	s_ashr_i32 s5, s4, 31
	s_lshr_b32 s7, s5, 27
	s_add_i32 s7, s4, s7
	s_ashr_i32 s8, s7, 5
	s_lshr_b32 s9, s8, 30
	s_add_i32 s9, s8, s9
	s_and_b32 s9, s9, 0x3fffffc
	s_and_b32 s7, s7, 0x1ffffe0
	s_sub_i32 s8, s8, s9
	s_lshr_b32 s5, s5, 25
	s_sub_i32 s7, s4, s7
	s_add_i32 s4, s4, s5
	s_lshl_b32 s8, s8, 6
	s_ashr_i32 s4, s4, 7
	s_ashr_i32 s9, s8, 31
	s_lshl_b32 s7, s7, 7
	s_ashr_i32 s5, s4, 31
	s_lshl_b64 s[8:9], s[8:9], 1
	v_readlane_b32 s10, v253, 56
	v_readlane_b32 s11, v253, 57
	s_add_u32 s10, s10, s8
	s_addc_u32 s11, s11, s9
	v_readlane_b32 s12, v253, 60
	v_mov_b32_e32 v16, v202
	s_waitcnt lgkmcnt(0)
	s_barrier
	v_readlane_b32 s13, v253, 61
	s_add_u32 s8, s12, s8
	s_addc_u32 s9, s13, s9
	v_ashrrev_i32_e32 v24, 3, v16
	s_add_i32 s12, s7, 0xffffff80
	v_min_i32_e32 v20, 0xff, v24
	v_add_u32_e32 v20, s12, v20
	v_ashrrev_i32_e32 v21, 31, v20
	s_lshl_b64 s[4:5], s[4:5], 20
	v_lshlrev_b32_e32 v16, 4, v16
	v_lshlrev_b64 v[20:21], 8, v[20:21]
	v_and_b32_e32 v112, 0x70, v16
	v_lshl_add_u64 v[20:21], v[20:21], 0, s[4:5]
	v_lshl_add_u64 v[16:17], s[10:11], 0, v[112:113]
	v_lshl_add_u64 v[18:19], s[8:9], 0, v[112:113]
	v_lshlrev_b64 v[20:21], 1, v[20:21]
	v_lshl_add_u64 v[22:23], v[16:17], 0, v[20:21]
	v_lshl_add_u64 v[20:21], v[18:19], 0, v[20:21]
	global_load_dwordx4 v[114:117], v[22:23], off
	global_load_dwordx4 v[118:121], v[20:21], off
	v_min_i32_e32 v20, 0xbf, v24
	s_sub_i32 s8, s7, 64
	v_add_u32_e32 v20, s8, v20
	v_ashrrev_i32_e32 v21, 31, v20
	v_lshlrev_b64 v[20:21], 8, v[20:21]
	v_lshl_add_u64 v[20:21], v[20:21], 0, s[4:5]
	v_lshlrev_b64 v[20:21], 1, v[20:21]
	v_lshl_add_u64 v[22:23], v[16:17], 0, v[20:21]
	v_lshl_add_u64 v[20:21], v[18:19], 0, v[20:21]
	global_load_dwordx4 v[122:125], v[22:23], off
	global_load_dwordx4 v[126:129], v[20:21], off
	v_min_i32_e32 v20, 0x7f, v24
	v_add_u32_e32 v20, s7, v20
	v_ashrrev_i32_e32 v21, 31, v20
	v_lshlrev_b64 v[20:21], 8, v[20:21]
	v_lshl_add_u64 v[20:21], v[20:21], 0, s[4:5]
	v_lshlrev_b64 v[20:21], 1, v[20:21]
	v_lshl_add_u64 v[22:23], v[16:17], 0, v[20:21]
	v_lshl_add_u64 v[20:21], v[18:19], 0, v[20:21]
	global_load_dwordx4 v[130:133], v[22:23], off
	global_load_dwordx4 v[134:137], v[20:21], off
	v_min_i32_e32 v20, 63, v24
	v_add3_u32 v20, v20, s7, 64
	v_ashrrev_i32_e32 v21, 31, v20
	v_lshlrev_b64 v[20:21], 8, v[20:21]
	v_lshl_add_u64 v[20:21], v[20:21], 0, s[4:5]
	v_lshlrev_b64 v[20:21], 1, v[20:21]
	v_lshl_add_u64 v[22:23], v[16:17], 0, v[20:21]
	v_lshl_add_u64 v[20:21], v[18:19], 0, v[20:21]
	global_load_dwordx4 v[138:141], v[22:23], off
	global_load_dwordx4 v[142:145], v[20:21], off
	v_min_i32_e32 v20, -1, v24
	s_addk_i32 s7, 0x80
	v_add_u32_e32 v20, s7, v20
	v_ashrrev_i32_e32 v21, 31, v20
	v_lshlrev_b64 v[20:21], 8, v[20:21]
	v_lshl_add_u64 v[20:21], v[20:21], 0, s[4:5]
	v_lshlrev_b64 v[20:21], 1, v[20:21]
	v_lshl_add_u64 v[16:17], v[16:17], 0, v[20:21]
	v_lshl_add_u64 v[18:19], v[18:19], 0, v[20:21]
	global_load_dwordx4 v[146:149], v[16:17], off
	global_load_dwordx4 v[150:153], v[18:19], off
	v_lshlrev_b32_e32 v23, 1, v217
	v_readlane_b32 s10, v251, 17
	v_or_b32_e32 v24, 1, v23
	s_mov_b32 s4, 0
	s_waitcnt vmcnt(13)
	v_lshlrev_b64 v[16:17], 1, v[182:183]
	v_readlane_b32 s11, v251, 18
	v_lshrrev_b32_e32 v25, 3, v203
	v_lshlrev_b32_e32 v26, 7, v25
	v_lshlrev_b32_e32 v27, 2, v25
	v_add_u32_e32 v27, 0x10000, v27
	v_lshrrev_b32_e32 v28, 1, v25
	v_lshrrev_b32_e32 v29, 4, v25
	v_xor_b32_e32 v28, v28, v29
	v_and_b32_e32 v28, 15, v28
	v_xor_b32_e32 v28, v28, v23
	v_mov_b32_e32 v32, v25
	v_mov_b32_e32 v33, 0
	v_lshl_add_u64 v[30:31], s[82:83], 0, v[32:33]
	v_lshlrev_b64 v[30:31], 11, v[30:31]
	v_lshl_add_u64 v[30:31], s[10:11], 0, v[30:31]
	v_mov_b32_e32 v34, s91
	v_mov_b32_e32 v35, 0
	v_lshl_add_u64 v[30:31], v[34:35], 1, v[30:31]
	v_lshl_add_u64 v[30:31], v[30:31], 0, v[16:17]
	v_mov_b32_e32 v38, 0x20000
	v_mov_b32_e32 v39, 0
	v_lshl_add_u64 v[36:37], v[30:31], 0, v[38:39]
	global_load_dwordx4 v[40:43], v[30:31], off
	global_load_dwordx4 v[44:47], v[36:37], off
	global_load_dwordx4 v[48:51], v[30:31], off offset:128
	global_load_dwordx4 v[52:55], v[36:37], off offset:128
	global_load_dwordx4 v[56:59], v[30:31], off offset:256
	global_load_dwordx4 v[60:63], v[36:37], off offset:256
	global_load_dwordx4 v[64:67], v[30:31], off offset:384
	global_load_dwordx4 v[68:71], v[36:37], off offset:384
	v_lshl_add_u32 v83, v28, 3, v26
	ds_read_b64 v[72:73], v83
	v_xor_b32_e32 v84, 1, v28
	v_lshl_add_u32 v84, v84, 3, v26
	ds_read_b64 v[74:75], v84
	ds_read_b32 v76, v27
	v_xor_b32_e32 v83, 4, v28
	v_lshl_add_u32 v83, v83, 3, v26
	ds_read_b64 v[78:79], v83 offset:8192
	v_xor_b32_e32 v84, 5, v28
	v_lshl_add_u32 v84, v84, 3, v26
	ds_read_b64 v[80:81], v84 offset:8192
	ds_read_b32 v82, v27 offset:256
	s_waitcnt lgkmcnt(3)
	v_div_scale_f32 v154, s[8:9], v76, v76, 1.0
	v_rcp_f32_e32 v155, v154
	v_lshlrev_b32_e32 v88, 16, v72
	v_and_b32_e32 v89, 0xffff0000, v72
	v_fma_f32 v156, -v154, v155, 1.0
	v_fmac_f32_e32 v155, v156, v155
	v_div_scale_f32 v156, vcc, 1.0, v76, 1.0
	v_mul_f32_e32 v157, v156, v155
	v_fma_f32 v158, -v154, v157, v156
	v_fmac_f32_e32 v157, v158, v155
	v_fma_f32 v154, -v154, v157, v156
	v_div_fmas_f32 v154, v154, v155, v157
	v_div_fixup_f32 v160, v154, v76, 1.0
	v_lshlrev_b32_e32 v90, 16, v73
	v_and_b32_e32 v91, 0xffff0000, v73
	v_lshlrev_b32_e32 v92, 16, v74
	v_and_b32_e32 v93, 0xffff0000, v74
	v_lshlrev_b32_e32 v94, 16, v75
	v_and_b32_e32 v95, 0xffff0000, v75
	v_pk_mul_f32 v[88:89], v[160:161], v[88:89] op_sel_hi:[0,1]
	v_pk_mul_f32 v[90:91], v[160:161], v[90:91] op_sel_hi:[0,1]
	v_pk_mul_f32 v[92:93], v[160:161], v[92:93] op_sel_hi:[0,1]
	v_pk_mul_f32 v[94:95], v[160:161], v[94:95] op_sel_hi:[0,1]
	s_waitcnt vmcnt(7)
; #define LAS __attribute__((address_space(3)))
; __device__ __forceinline__ unsigned pkbf(float lo, float hi) { f32x2v v = {lo, hi}; return __builtin_bit_cast(unsigned, __builtin_convertvector(v, bf2_t)); }
; __device__ __forceinline__ float bflo(unsigned w) { return __uint_as_float(w << 16); }
; __device__ __forceinline__ float bfhi(unsigned w) { return __uint_as_float(w & 0xffff0000u); }
; template <int MIX, bool DRY = false>
; __device__ __forceinline__ void attn_phase(LAS unsigned char* lds, const bf16_t* Qb, const bf16_t* Kb, const bf16_t* Vb, bf16_t* Gb, const float* qg, const float* kg, const float* sinks) {
;     ...
;             for (int it = 0; it < (DRY ? 0 : 8); ++it) {
;                 const int item = it * 512 + tidu, row = item >> 3, dg = item & 7, hr = row / CT, tl = row % CT;
;                 const int f = ((tl >> 1) ^ (tl >> 4) ^ (hr << 2)) & 15, head = kvh * REP + hr;
;                 const LAS unsigned char* orow = Oacc + row * 128;
;                 const u32x2 o0 = *(const LAS u32x2*)(orow + (((2 * dg) ^ f) << 3)), o1 = *(const LAS u32x2*)(orow + (((2 * dg + 1) ^ f) << 3));
;                 const float inv = 1.0f / lacc[row];
;                 u32x4* gp = (u32x4*)(Gb + (rowb + t0 + tl) * 1024 + head * 64 + 8 * dg);
;                 const u32x4 gv = *gp;
;                 u32x4 w;
;                 w.x = pkbf(bflo(o0.x) * inv * bflo(gv.x), bfhi(o0.x) * inv * bfhi(gv.x)); w.y = pkbf(bflo(o0.y) * inv * bflo(gv.y), bfhi(o0.y) * inv * bfhi(gv.y));
;                 w.z = pkbf(bflo(o1.x) * inv * bflo(gv.z), bfhi(o1.x) * inv * bfhi(gv.z)); w.w = pkbf(bflo(o1.y) * inv * bflo(gv.w), bfhi(o1.y) * inv * bfhi(gv.w));
;                 *gp = w;
	v_lshlrev_b32_e32 v96, 16, v40
	v_and_b32_e32 v97, 0xffff0000, v40
	v_pk_mul_f32 v[88:89], v[88:89], v[96:97]
	v_lshlrev_b32_e32 v96, 16, v41
	v_and_b32_e32 v97, 0xffff0000, v41
	v_pk_mul_f32 v[90:91], v[90:91], v[96:97]
	v_lshlrev_b32_e32 v96, 16, v42
	v_and_b32_e32 v97, 0xffff0000, v42
	v_pk_mul_f32 v[92:93], v[92:93], v[96:97]
	v_lshlrev_b32_e32 v96, 16, v43
	v_and_b32_e32 v97, 0xffff0000, v43
	v_pk_mul_f32 v[94:95], v[94:95], v[96:97]
	v_cvt_pk_bf16_f32 v100, v88, v89
	v_cvt_pk_bf16_f32 v101, v90, v91
	v_cvt_pk_bf16_f32 v102, v92, v93
	v_cvt_pk_bf16_f32 v103, v94, v95
	global_store_dwordx4 v[30:31], v[100:103], off
	v_xor_b32_e32 v83, 4, v28
	v_lshl_add_u32 v83, v83, 3, v26
	ds_read_b64 v[72:73], v83 offset:16384
	v_xor_b32_e32 v84, 5, v28
	v_lshl_add_u32 v84, v84, 3, v26
	ds_read_b64 v[74:75], v84 offset:16384
	ds_read_b32 v76, v27 offset:512
	s_waitcnt lgkmcnt(3)
	v_div_scale_f32 v154, s[8:9], v82, v82, 1.0
	v_rcp_f32_e32 v155, v154
	v_lshlrev_b32_e32 v88, 16, v78
	v_and_b32_e32 v89, 0xffff0000, v78
	v_fma_f32 v156, -v154, v155, 1.0
	v_fmac_f32_e32 v155, v156, v155
	v_div_scale_f32 v156, vcc, 1.0, v82, 1.0
	v_mul_f32_e32 v157, v156, v155
	v_fma_f32 v158, -v154, v157, v156
	v_fmac_f32_e32 v157, v158, v155
	v_fma_f32 v154, -v154, v157, v156
	v_div_fmas_f32 v154, v154, v155, v157
	v_div_fixup_f32 v160, v154, v82, 1.0
	v_lshlrev_b32_e32 v90, 16, v79
	v_and_b32_e32 v91, 0xffff0000, v79
	v_lshlrev_b32_e32 v92, 16, v80
	v_and_b32_e32 v93, 0xffff0000, v80
	v_lshlrev_b32_e32 v94, 16, v81
	v_and_b32_e32 v95, 0xffff0000, v81
	v_pk_mul_f32 v[88:89], v[160:161], v[88:89] op_sel_hi:[0,1]
	v_pk_mul_f32 v[90:91], v[160:161], v[90:91] op_sel_hi:[0,1]
	v_pk_mul_f32 v[92:93], v[160:161], v[92:93] op_sel_hi:[0,1]
	v_pk_mul_f32 v[94:95], v[160:161], v[94:95] op_sel_hi:[0,1]
	s_waitcnt vmcnt(7)
	v_lshlrev_b32_e32 v96, 16, v44
	v_and_b32_e32 v97, 0xffff0000, v44
	v_pk_mul_f32 v[88:89], v[88:89], v[96:97]
	v_lshlrev_b32_e32 v96, 16, v45
	v_and_b32_e32 v97, 0xffff0000, v45
	v_pk_mul_f32 v[90:91], v[90:91], v[96:97]
	v_lshlrev_b32_e32 v96, 16, v46
	v_and_b32_e32 v97, 0xffff0000, v46
	v_pk_mul_f32 v[92:93], v[92:93], v[96:97]
	v_lshlrev_b32_e32 v96, 16, v47
	v_and_b32_e32 v97, 0xffff0000, v47
	v_pk_mul_f32 v[94:95], v[94:95], v[96:97]
	v_cvt_pk_bf16_f32 v104, v88, v89
	v_cvt_pk_bf16_f32 v105, v90, v91
	v_cvt_pk_bf16_f32 v106, v92, v93
	v_cvt_pk_bf16_f32 v107, v94, v95
	global_store_dwordx4 v[36:37], v[104:107], off
	v_lshl_add_u32 v83, v28, 3, v26
	ds_read_b64 v[78:79], v83 offset:24576
	v_xor_b32_e32 v84, 1, v28
	v_lshl_add_u32 v84, v84, 3, v26
	ds_read_b64 v[80:81], v84 offset:24576
	ds_read_b32 v82, v27 offset:768
	s_waitcnt lgkmcnt(3)
	v_div_scale_f32 v154, s[8:9], v76, v76, 1.0
	v_rcp_f32_e32 v155, v154
	v_lshlrev_b32_e32 v88, 16, v72
	v_and_b32_e32 v89, 0xffff0000, v72
	v_fma_f32 v156, -v154, v155, 1.0
	v_fmac_f32_e32 v155, v156, v155
	v_div_scale_f32 v156, vcc, 1.0, v76, 1.0
	v_mul_f32_e32 v157, v156, v155
	v_fma_f32 v158, -v154, v157, v156
	v_fmac_f32_e32 v157, v158, v155
	v_fma_f32 v154, -v154, v157, v156
	v_div_fmas_f32 v154, v154, v155, v157
	v_div_fixup_f32 v160, v154, v76, 1.0
	v_lshlrev_b32_e32 v90, 16, v73
	v_and_b32_e32 v91, 0xffff0000, v73
	v_lshlrev_b32_e32 v92, 16, v74
	v_and_b32_e32 v93, 0xffff0000, v74
	v_lshlrev_b32_e32 v94, 16, v75
	v_and_b32_e32 v95, 0xffff0000, v75
	v_pk_mul_f32 v[88:89], v[160:161], v[88:89] op_sel_hi:[0,1]
	v_pk_mul_f32 v[90:91], v[160:161], v[90:91] op_sel_hi:[0,1]
	v_pk_mul_f32 v[92:93], v[160:161], v[92:93] op_sel_hi:[0,1]
	v_pk_mul_f32 v[94:95], v[160:161], v[94:95] op_sel_hi:[0,1]
	s_waitcnt vmcnt(7)
	v_lshlrev_b32_e32 v96, 16, v48
	v_and_b32_e32 v97, 0xffff0000, v48
	v_pk_mul_f32 v[88:89], v[88:89], v[96:97]
	v_lshlrev_b32_e32 v96, 16, v49
	v_and_b32_e32 v97, 0xffff0000, v49
	v_pk_mul_f32 v[90:91], v[90:91], v[96:97]
	v_lshlrev_b32_e32 v96, 16, v50
	v_and_b32_e32 v97, 0xffff0000, v50
	v_pk_mul_f32 v[92:93], v[92:93], v[96:97]
	v_lshlrev_b32_e32 v96, 16, v51
	v_and_b32_e32 v97, 0xffff0000, v51
	v_pk_mul_f32 v[94:95], v[94:95], v[96:97]
	v_cvt_pk_bf16_f32 v100, v88, v89
	v_cvt_pk_bf16_f32 v101, v90, v91
	v_cvt_pk_bf16_f32 v102, v92, v93
	v_cvt_pk_bf16_f32 v103, v94, v95
	global_store_dwordx4 v[30:31], v[100:103], off offset:128
	v_xor_b32_e32 v83, 8, v28
	v_lshl_add_u32 v83, v83, 3, v26
	ds_read_b64 v[72:73], v83 offset:32768
	v_xor_b32_e32 v84, 9, v28
	v_lshl_add_u32 v84, v84, 3, v26
	ds_read_b64 v[74:75], v84 offset:32768
	ds_read_b32 v76, v27 offset:1024
	s_waitcnt lgkmcnt(3)
	v_div_scale_f32 v154, s[8:9], v82, v82, 1.0
	v_rcp_f32_e32 v155, v154
	v_lshlrev_b32_e32 v88, 16, v78
	v_and_b32_e32 v89, 0xffff0000, v78
	v_fma_f32 v156, -v154, v155, 1.0
	v_fmac_f32_e32 v155, v156, v155
	v_div_scale_f32 v156, vcc, 1.0, v82, 1.0
	v_mul_f32_e32 v157, v156, v155
	v_fma_f32 v158, -v154, v157, v156
	v_fmac_f32_e32 v157, v158, v155
	v_fma_f32 v154, -v154, v157, v156
	v_div_fmas_f32 v154, v154, v155, v157
	v_div_fixup_f32 v160, v154, v82, 1.0
	v_lshlrev_b32_e32 v90, 16, v79
	v_and_b32_e32 v91, 0xffff0000, v79
	v_lshlrev_b32_e32 v92, 16, v80
	v_and_b32_e32 v93, 0xffff0000, v80
	v_lshlrev_b32_e32 v94, 16, v81
	v_and_b32_e32 v95, 0xffff0000, v81
	v_pk_mul_f32 v[88:89], v[160:161], v[88:89] op_sel_hi:[0,1]
	v_pk_mul_f32 v[90:91], v[160:161], v[90:91] op_sel_hi:[0,1]
	v_pk_mul_f32 v[92:93], v[160:161], v[92:93] op_sel_hi:[0,1]
	v_pk_mul_f32 v[94:95], v[160:161], v[94:95] op_sel_hi:[0,1]
	s_waitcnt vmcnt(7)
; #define LAS __attribute__((address_space(3)))
; __device__ __forceinline__ unsigned pkbf(float lo, float hi) { f32x2v v = {lo, hi}; return __builtin_bit_cast(unsigned, __builtin_convertvector(v, bf2_t)); }
; __device__ __forceinline__ float bflo(unsigned w) { return __uint_as_float(w << 16); }
; __device__ __forceinline__ float bfhi(unsigned w) { return __uint_as_float(w & 0xffff0000u); }
; template <int MIX, bool DRY = false>
; __device__ __forceinline__ void attn_phase(LAS unsigned char* lds, const bf16_t* Qb, const bf16_t* Kb, const bf16_t* Vb, bf16_t* Gb, const float* qg, const float* kg, const float* sinks) {
;     ...
;             for (int it = 0; it < (DRY ? 0 : 8); ++it) {
;                 const int item = it * 512 + tidu, row = item >> 3, dg = item & 7, hr = row / CT, tl = row % CT;
;                 const int f = ((tl >> 1) ^ (tl >> 4) ^ (hr << 2)) & 15, head = kvh * REP + hr;
;                 const LAS unsigned char* orow = Oacc + row * 128;
;                 const u32x2 o0 = *(const LAS u32x2*)(orow + (((2 * dg) ^ f) << 3)), o1 = *(const LAS u32x2*)(orow + (((2 * dg + 1) ^ f) << 3));
;                 const float inv = 1.0f / lacc[row];
;                 u32x4* gp = (u32x4*)(Gb + (rowb + t0 + tl) * 1024 + head * 64 + 8 * dg);
;                 const u32x4 gv = *gp;
;                 u32x4 w;
;                 w.x = pkbf(bflo(o0.x) * inv * bflo(gv.x), bfhi(o0.x) * inv * bfhi(gv.x)); w.y = pkbf(bflo(o0.y) * inv * bflo(gv.y), bfhi(o0.y) * inv * bfhi(gv.y));
;                 w.z = pkbf(bflo(o1.x) * inv * bflo(gv.z), bfhi(o1.x) * inv * bfhi(gv.z)); w.w = pkbf(bflo(o1.y) * inv * bflo(gv.w), bfhi(o1.y) * inv * bfhi(gv.w));
;                 *gp = w;
	v_lshlrev_b32_e32 v96, 16, v52
	v_and_b32_e32 v97, 0xffff0000, v52
	v_pk_mul_f32 v[88:89], v[88:89], v[96:97]
	v_lshlrev_b32_e32 v96, 16, v53
	v_and_b32_e32 v97, 0xffff0000, v53
	v_pk_mul_f32 v[90:91], v[90:91], v[96:97]
	v_lshlrev_b32_e32 v96, 16, v54
	v_and_b32_e32 v97, 0xffff0000, v54
	v_pk_mul_f32 v[92:93], v[92:93], v[96:97]
	v_lshlrev_b32_e32 v96, 16, v55
	v_and_b32_e32 v97, 0xffff0000, v55
	v_pk_mul_f32 v[94:95], v[94:95], v[96:97]
	v_cvt_pk_bf16_f32 v104, v88, v89
	v_cvt_pk_bf16_f32 v105, v90, v91
	v_cvt_pk_bf16_f32 v106, v92, v93
	v_cvt_pk_bf16_f32 v107, v94, v95
	global_store_dwordx4 v[36:37], v[104:107], off offset:128
	v_xor_b32_e32 v83, 12, v28
	v_lshl_add_u32 v83, v83, 3, v26
	ds_read_b64 v[78:79], v83 offset:40960
	v_xor_b32_e32 v84, 13, v28
	v_lshl_add_u32 v84, v84, 3, v26
	ds_read_b64 v[80:81], v84 offset:40960
	ds_read_b32 v82, v27 offset:1280
	s_waitcnt lgkmcnt(3)
	v_div_scale_f32 v154, s[8:9], v76, v76, 1.0
	v_rcp_f32_e32 v155, v154
	v_lshlrev_b32_e32 v88, 16, v72
	v_and_b32_e32 v89, 0xffff0000, v72
	v_fma_f32 v156, -v154, v155, 1.0
	v_fmac_f32_e32 v155, v156, v155
	v_div_scale_f32 v156, vcc, 1.0, v76, 1.0
	v_mul_f32_e32 v157, v156, v155
	v_fma_f32 v158, -v154, v157, v156
	v_fmac_f32_e32 v157, v158, v155
	v_fma_f32 v154, -v154, v157, v156
	v_div_fmas_f32 v154, v154, v155, v157
	v_div_fixup_f32 v160, v154, v76, 1.0
	v_lshlrev_b32_e32 v90, 16, v73
	v_and_b32_e32 v91, 0xffff0000, v73
	v_lshlrev_b32_e32 v92, 16, v74
	v_and_b32_e32 v93, 0xffff0000, v74
	v_lshlrev_b32_e32 v94, 16, v75
	v_and_b32_e32 v95, 0xffff0000, v75
	v_pk_mul_f32 v[88:89], v[160:161], v[88:89] op_sel_hi:[0,1]
	v_pk_mul_f32 v[90:91], v[160:161], v[90:91] op_sel_hi:[0,1]
	v_pk_mul_f32 v[92:93], v[160:161], v[92:93] op_sel_hi:[0,1]
	v_pk_mul_f32 v[94:95], v[160:161], v[94:95] op_sel_hi:[0,1]
	s_waitcnt vmcnt(7)
	v_lshlrev_b32_e32 v96, 16, v56
	v_and_b32_e32 v97, 0xffff0000, v56
	v_pk_mul_f32 v[88:89], v[88:89], v[96:97]
	v_lshlrev_b32_e32 v96, 16, v57
	v_and_b32_e32 v97, 0xffff0000, v57
	v_pk_mul_f32 v[90:91], v[90:91], v[96:97]
	v_lshlrev_b32_e32 v96, 16, v58
	v_and_b32_e32 v97, 0xffff0000, v58
	v_pk_mul_f32 v[92:93], v[92:93], v[96:97]
	v_lshlrev_b32_e32 v96, 16, v59
	v_and_b32_e32 v97, 0xffff0000, v59
	v_pk_mul_f32 v[94:95], v[94:95], v[96:97]
	v_cvt_pk_bf16_f32 v100, v88, v89
	v_cvt_pk_bf16_f32 v101, v90, v91
	v_cvt_pk_bf16_f32 v102, v92, v93
	v_cvt_pk_bf16_f32 v103, v94, v95
	global_store_dwordx4 v[30:31], v[100:103], off offset:256
	v_xor_b32_e32 v83, 12, v28
	v_lshl_add_u32 v83, v83, 3, v26
	ds_read_b64 v[72:73], v83 offset:49152
	v_xor_b32_e32 v84, 13, v28
	v_lshl_add_u32 v84, v84, 3, v26
	ds_read_b64 v[74:75], v84 offset:49152
	ds_read_b32 v76, v27 offset:1536
	s_waitcnt lgkmcnt(3)
	v_div_scale_f32 v154, s[8:9], v82, v82, 1.0
	v_rcp_f32_e32 v155, v154
	v_lshlrev_b32_e32 v88, 16, v78
	v_and_b32_e32 v89, 0xffff0000, v78
	v_fma_f32 v156, -v154, v155, 1.0
	v_fmac_f32_e32 v155, v156, v155
	v_div_scale_f32 v156, vcc, 1.0, v82, 1.0
	v_mul_f32_e32 v157, v156, v155
	v_fma_f32 v158, -v154, v157, v156
	v_fmac_f32_e32 v157, v158, v155
	v_fma_f32 v154, -v154, v157, v156
	v_div_fmas_f32 v154, v154, v155, v157
	v_div_fixup_f32 v160, v154, v82, 1.0
	v_lshlrev_b32_e32 v90, 16, v79
	v_and_b32_e32 v91, 0xffff0000, v79
	v_lshlrev_b32_e32 v92, 16, v80
	v_and_b32_e32 v93, 0xffff0000, v80
	v_lshlrev_b32_e32 v94, 16, v81
	v_and_b32_e32 v95, 0xffff0000, v81
	v_pk_mul_f32 v[88:89], v[160:161], v[88:89] op_sel_hi:[0,1]
	v_pk_mul_f32 v[90:91], v[160:161], v[90:91] op_sel_hi:[0,1]
	v_pk_mul_f32 v[92:93], v[160:161], v[92:93] op_sel_hi:[0,1]
	v_pk_mul_f32 v[94:95], v[160:161], v[94:95] op_sel_hi:[0,1]
	s_waitcnt vmcnt(7)
	v_lshlrev_b32_e32 v96, 16, v60
	v_and_b32_e32 v97, 0xffff0000, v60
	v_pk_mul_f32 v[88:89], v[88:89], v[96:97]
	v_lshlrev_b32_e32 v96, 16, v61
	v_and_b32_e32 v97, 0xffff0000, v61
	v_pk_mul_f32 v[90:91], v[90:91], v[96:97]
	v_lshlrev_b32_e32 v96, 16, v62
	v_and_b32_e32 v97, 0xffff0000, v62
	v_pk_mul_f32 v[92:93], v[92:93], v[96:97]
	v_lshlrev_b32_e32 v96, 16, v63
	v_and_b32_e32 v97, 0xffff0000, v63
	v_pk_mul_f32 v[94:95], v[94:95], v[96:97]
	v_cvt_pk_bf16_f32 v104, v88, v89
	v_cvt_pk_bf16_f32 v105, v90, v91
	v_cvt_pk_bf16_f32 v106, v92, v93
	v_cvt_pk_bf16_f32 v107, v94, v95
	global_store_dwordx4 v[36:37], v[104:107], off offset:256
	v_xor_b32_e32 v83, 8, v28
	v_lshl_add_u32 v83, v83, 3, v26
	ds_read_b64 v[78:79], v83 offset:57344
	v_xor_b32_e32 v84, 9, v28
	v_lshl_add_u32 v84, v84, 3, v26
	ds_read_b64 v[80:81], v84 offset:57344
	ds_read_b32 v82, v27 offset:1792
	s_waitcnt lgkmcnt(3)
; #define LAS __attribute__((address_space(3)))
; __device__ __forceinline__ unsigned pkbf(float lo, float hi) { f32x2v v = {lo, hi}; return __builtin_bit_cast(unsigned, __builtin_convertvector(v, bf2_t)); }
; __device__ __forceinline__ float bflo(unsigned w) { return __uint_as_float(w << 16); }
; __device__ __forceinline__ float bfhi(unsigned w) { return __uint_as_float(w & 0xffff0000u); }
; template <int MIX, bool DRY = false>
; __device__ __forceinline__ void attn_phase(LAS unsigned char* lds, const bf16_t* Qb, const bf16_t* Kb, const bf16_t* Vb, bf16_t* Gb, const float* qg, const float* kg, const float* sinks) {
;     ...
;             for (int it = 0; it < (DRY ? 0 : 8); ++it) {
;                 const int item = it * 512 + tidu, row = item >> 3, dg = item & 7, hr = row / CT, tl = row % CT;
;                 const int f = ((tl >> 1) ^ (tl >> 4) ^ (hr << 2)) & 15, head = kvh * REP + hr;
;                 const LAS unsigned char* orow = Oacc + row * 128;
;                 const u32x2 o0 = *(const LAS u32x2*)(orow + (((2 * dg) ^ f) << 3)), o1 = *(const LAS u32x2*)(orow + (((2 * dg + 1) ^ f) << 3));
;                 const float inv = 1.0f / lacc[row];
;                 u32x4* gp = (u32x4*)(Gb + (rowb + t0 + tl) * 1024 + head * 64 + 8 * dg);
;                 const u32x4 gv = *gp;
;                 u32x4 w;
;                 w.x = pkbf(bflo(o0.x) * inv * bflo(gv.x), bfhi(o0.x) * inv * bfhi(gv.x)); w.y = pkbf(bflo(o0.y) * inv * bflo(gv.y), bfhi(o0.y) * inv * bfhi(gv.y));
;                 w.z = pkbf(bflo(o1.x) * inv * bflo(gv.z), bfhi(o1.x) * inv * bfhi(gv.z)); w.w = pkbf(bflo(o1.y) * inv * bflo(gv.w), bfhi(o1.y) * inv * bfhi(gv.w));
;                 *gp = w;
;             }
;             if (more) STAGE_STORE(0)
	v_div_scale_f32 v154, s[8:9], v76, v76, 1.0
	v_rcp_f32_e32 v155, v154
	v_lshlrev_b32_e32 v88, 16, v72
	v_and_b32_e32 v89, 0xffff0000, v72
	v_fma_f32 v156, -v154, v155, 1.0
	v_fmac_f32_e32 v155, v156, v155
	v_div_scale_f32 v156, vcc, 1.0, v76, 1.0
	v_mul_f32_e32 v157, v156, v155
	v_fma_f32 v158, -v154, v157, v156
	v_fmac_f32_e32 v157, v158, v155
	v_fma_f32 v154, -v154, v157, v156
	v_div_fmas_f32 v154, v154, v155, v157
	v_div_fixup_f32 v160, v154, v76, 1.0
	v_lshlrev_b32_e32 v90, 16, v73
	v_and_b32_e32 v91, 0xffff0000, v73
	v_lshlrev_b32_e32 v92, 16, v74
	v_and_b32_e32 v93, 0xffff0000, v74
	v_lshlrev_b32_e32 v94, 16, v75
	v_and_b32_e32 v95, 0xffff0000, v75
	v_pk_mul_f32 v[88:89], v[160:161], v[88:89] op_sel_hi:[0,1]
	v_pk_mul_f32 v[90:91], v[160:161], v[90:91] op_sel_hi:[0,1]
	v_pk_mul_f32 v[92:93], v[160:161], v[92:93] op_sel_hi:[0,1]
	v_pk_mul_f32 v[94:95], v[160:161], v[94:95] op_sel_hi:[0,1]
	s_waitcnt vmcnt(7)
	v_lshlrev_b32_e32 v96, 16, v64
	v_and_b32_e32 v97, 0xffff0000, v64
	v_pk_mul_f32 v[88:89], v[88:89], v[96:97]
	v_lshlrev_b32_e32 v96, 16, v65
	v_and_b32_e32 v97, 0xffff0000, v65
	v_pk_mul_f32 v[90:91], v[90:91], v[96:97]
	v_lshlrev_b32_e32 v96, 16, v66
	v_and_b32_e32 v97, 0xffff0000, v66
	v_pk_mul_f32 v[92:93], v[92:93], v[96:97]
	v_lshlrev_b32_e32 v96, 16, v67
	v_and_b32_e32 v97, 0xffff0000, v67
	v_pk_mul_f32 v[94:95], v[94:95], v[96:97]
	v_cvt_pk_bf16_f32 v100, v88, v89
	v_cvt_pk_bf16_f32 v101, v90, v91
	v_cvt_pk_bf16_f32 v102, v92, v93
	v_cvt_pk_bf16_f32 v103, v94, v95
	global_store_dwordx4 v[30:31], v[100:103], off offset:384
	s_waitcnt lgkmcnt(0)
	v_div_scale_f32 v154, s[8:9], v82, v82, 1.0
	v_rcp_f32_e32 v155, v154
	v_lshlrev_b32_e32 v88, 16, v78
	v_and_b32_e32 v89, 0xffff0000, v78
	v_fma_f32 v156, -v154, v155, 1.0
	v_fmac_f32_e32 v155, v156, v155
	v_div_scale_f32 v156, vcc, 1.0, v82, 1.0
	v_mul_f32_e32 v157, v156, v155
	v_fma_f32 v158, -v154, v157, v156
	v_fmac_f32_e32 v157, v158, v155
	v_fma_f32 v154, -v154, v157, v156
	v_div_fmas_f32 v154, v154, v155, v157
	v_div_fixup_f32 v160, v154, v82, 1.0
	v_lshlrev_b32_e32 v90, 16, v79
	v_and_b32_e32 v91, 0xffff0000, v79
	v_lshlrev_b32_e32 v92, 16, v80
	v_and_b32_e32 v93, 0xffff0000, v80
	v_lshlrev_b32_e32 v94, 16, v81
	v_and_b32_e32 v95, 0xffff0000, v81
	v_pk_mul_f32 v[88:89], v[160:161], v[88:89] op_sel_hi:[0,1]
	v_pk_mul_f32 v[90:91], v[160:161], v[90:91] op_sel_hi:[0,1]
	v_pk_mul_f32 v[92:93], v[160:161], v[92:93] op_sel_hi:[0,1]
	v_pk_mul_f32 v[94:95], v[160:161], v[94:95] op_sel_hi:[0,1]
	s_waitcnt vmcnt(7)
	v_lshlrev_b32_e32 v96, 16, v68
	v_and_b32_e32 v97, 0xffff0000, v68
	v_pk_mul_f32 v[88:89], v[88:89], v[96:97]
	v_lshlrev_b32_e32 v96, 16, v69
	v_and_b32_e32 v97, 0xffff0000, v69
	v_pk_mul_f32 v[90:91], v[90:91], v[96:97]
	v_lshlrev_b32_e32 v96, 16, v70
	v_and_b32_e32 v97, 0xffff0000, v70
	v_pk_mul_f32 v[92:93], v[92:93], v[96:97]
	v_lshlrev_b32_e32 v96, 16, v71
	v_and_b32_e32 v97, 0xffff0000, v71
	v_pk_mul_f32 v[94:95], v[94:95], v[96:97]
	v_cvt_pk_bf16_f32 v104, v88, v89
	v_cvt_pk_bf16_f32 v105, v90, v91
	v_cvt_pk_bf16_f32 v106, v92, v93
	v_cvt_pk_bf16_f32 v107, v94, v95
	global_store_dwordx4 v[36:37], v[104:107], off offset:384
	v_readlane_b32 s82, v251, 47
	s_mov_b64 s[4:5], -1
	s_and_b64 vcc, exec, s[0:1]
	v_readlane_b32 s83, v251, 48
	v_readlane_b32 s91, v251, 49
	s_cbranch_vccz .LBB0_407
	ds_write_b128 v237, v[114:117]
	ds_write_b128 v238, v[118:121]
	ds_write_b128 v237, v[122:125] offset:8192
	ds_write_b128 v238, v[126:129] offset:8192
	ds_write_b128 v237, v[130:133] offset:16384
	ds_write_b128 v238, v[134:137] offset:16384
	ds_write_b128 v237, v[138:141] offset:24576
	ds_write_b128 v238, v[142:145] offset:24576
	s_branch .LBB0_406
